# plus MLA q up-projection rope epilogues: rope table loads hoisted (two 16-row blocks)
# baseline (speedup 1.0000x reference)
; #define MFMA(a, b, c) __builtin_amdgcn_mfma_f32_32x32x16_bf16((a), (b), (c), 0, 0, 0)
; DI void gt_compute(const bf16* asr, const bf16* bsr, f32x16& acc0, f32x16& acc1, f32x16& acc2, f32x16& acc3) {
;   bf16x8 a[4], b0[4], b1[4], b2[4], b3[4];
; #pragma unroll
;   for (int kk = 0; kk < 4; ++kk) {
;     a[kk] = *(const bf16x8*)(asr + kk * 16);
;     b0[kk] = *(const bf16x8*)(bsr + kk * 16);
;     b1[kk] = *(const bf16x8*)(bsr + 32 * LDT + kk * 16);
;     b2[kk] = *(const bf16x8*)(bsr + 64 * LDT + kk * 16);
;     b3[kk] = *(const bf16x8*)(bsr + 96 * LDT + kk * 16);
;   }
;   __builtin_amdgcn_sched_barrier(0);
;   __builtin_amdgcn_s_setprio(2);
; #pragma unroll
;   for (int kk = 0; kk < 4; ++kk) {
;     acc0 = MFMA(a[kk], b0[kk], acc0); acc1 = MFMA(a[kk], b1[kk], acc1); acc2 = MFMA(a[kk], b2[kk], acc2); acc3 = MFMA(a[kk], b3[kk], acc3);
;   }
;   __builtin_amdgcn_s_setprio(0);
;   __builtin_amdgcn_sched_barrier(0);
; DI void gemm_mainloop(const bf16* __restrict__ A, int lda, const bf16* __restrict__ Bt, int ldb, int K, int m0, int n0,
;                       bf16* As, bf16* Bs, f32x16& acc0, f32x16& acc1, f32x16& acc2, f32x16& acc3) {
;   const int tid = opaque_tid(), lane = tid & 63, w = tid >> 6, r = lane & 31, g = lane >> 5;
;   const int lrow = tid >> 3, lcc = (tid & 7) * 8;
;   const bf16* ap = A + (size_t)(m0 + lrow) * lda + lcc;
;   const bf16* bp = Bt + (size_t)(n0 + lrow) * ldb + lcc;
;   GTile t0, t1;
;   asm volatile("" ::: "memory");
;   const int nkt = K >> 6;
;   int kb = ((((m0 >> 7) * 5 + (n0 >> 7) * 3) >> 1) % nkt) << 6;
;     ...
;   gt_load(t0, ap, bp, lda, ldb, KW(0));
;   gt_load(t1, ap, bp, lda, ldb, KW(64));
; #pragma unroll
;   for (int i = 0; i < 16; ++i) { acc0[i] = 0.f; acc1[i] = 0.f; acc2[i] = 0.f; acc3[i] = 0.f; }
;   bf16* asw = As + lrow * LDT + lcc;
;   bf16* bsw = Bs + lrow * LDT + lcc;
;   const bf16* asr = As + (32 * w + r) * LDT + g * 8;
;   const bf16* bsr = Bs + r * LDT + g * 8;
;   for (int k0 = 0; k0 < K; k0 += 128) {
;     __syncthreads();
;     gt_store(t0, asw, bsw);
;     __syncthreads();
;     if (k0 + 128 < K) gt_load(t0, ap, bp, lda, ldb, KW(k0 + 128));
;     gt_compute(asr, bsr, acc0, acc1, acc2, acc3);
;     __syncthreads();
;     gt_store(t1, asw, bsw);
;     __syncthreads();
;     if (k0 + 192 < K) gt_load(t1, ap, bp, lda, ldb, KW(k0 + 192));
;     gt_compute(asr, bsr, acc0, acc1, acc2, acc3);
.LBB0_325:
	s_or_b64 exec, exec, s[12:13]
	v_mov_b32_e32 v40, v160
	s_mul_i32 s43, s14, 0x600
	v_ashrrev_i32_e32 v41, 3, v40
	v_lshlrev_b32_e32 v2, 4, v40
	v_and_b32_e32 v68, 0x70, v2
	v_subrev_u32_e32 v2, s43, v41
	v_add_u32_e32 v2, s4, v2
	v_add_u32_e32 v0, s15, v41
	v_add_u32_e32 v2, 0xffffffa0, v2
	v_mad_i64_i32 v[0:1], s[0:1], v0, s19, v[72:73]
	v_mad_i64_i32 v[2:3], s[0:1], v2, s20, v[74:75]
	s_mul_i32 s0, s14, 0xffffffe1
	s_add_i32 s0, s16, s0
	s_ashr_i32 s0, s0, 1
	s_mul_hi_i32 s1, s0, 0x2aaaaaab
	s_lshr_b32 s12, s1, 31
	s_add_i32 s1, s1, s12
	s_mul_i32 s1, s1, 6
	s_sub_i32 s0, s0, s1
	s_lshl_b32 s12, s0, 6
	s_ashr_i32 s13, s12, 31
	v_lshl_add_u64 v[0:1], v[0:1], 0, v[68:69]
	s_lshl_b64 s[12:13], s[12:13], 1
	v_lshl_add_u64 v[76:77], v[0:1], 0, s[12:13]
	v_add_co_u32_e32 v8, vcc, s21, v76
	v_lshl_add_u64 v[2:3], v[2:3], 0, v[68:69]
	s_nop 0
	v_addc_co_u32_e32 v9, vcc, 0, v77, vcc
	v_add_co_u32_e32 v10, vcc, s28, v76
	v_lshl_add_u64 v[78:79], v[2:3], 0, s[12:13]
	s_nop 0
	v_addc_co_u32_e32 v11, vcc, 0, v77, vcc
	v_add_co_u32_e32 v16, vcc, s29, v76
	global_load_dwordx4 v[0:3], v[8:9], off
	global_load_dwordx4 v[4:7], v[10:11], off
	v_addc_co_u32_e32 v17, vcc, 0, v77, vcc
	v_add_co_u32_e32 v20, vcc, s34, v78
	global_load_dwordx4 v[8:11], v[76:77], off
	global_load_dwordx4 v[12:15], v[78:79], off
	v_addc_co_u32_e32 v21, vcc, 0, v79, vcc
	v_add_co_u32_e32 v24, vcc, s35, v78
	global_load_dwordx4 v[16:19], v[16:17], off
	s_nop 0
	global_load_dwordx4 v[20:23], v[20:21], off
	v_addc_co_u32_e32 v25, vcc, 0, v79, vcc
	v_add_co_u32_e32 v28, vcc, s38, v78
	s_mul_i32 s1, s14, 0xfffffa00
	s_nop 0
	v_addc_co_u32_e32 v29, vcc, 0, v79, vcc
	global_load_dwordx4 v[24:27], v[24:25], off
	s_nop 0
	global_load_dwordx4 v[28:31], v[28:29], off
	s_add_i32 s44, s4, s1
	s_add_i32 s12, s44, 0xffffffa0
	s_cmp_lt_i32 s0, 5
	s_cselect_b32 s47, 0, -1
	s_cselect_b32 s46, 0, 0xfffffd00
	v_lshl_add_u64 v[32:33], v[76:77], 0, s[46:47]
	v_add_co_u32_e32 v36, vcc, s21, v32
	v_lshl_add_u64 v[34:35], v[78:79], 0, s[46:47]
	s_nop 0
	v_addc_co_u32_e32 v37, vcc, 0, v33, vcc
	v_add_co_u32_e32 v38, vcc, s28, v32
	v_mad_u64_u32 v[64:65], s[46:47], v41, s39, v[68:69]
	s_nop 0
	v_addc_co_u32_e32 v39, vcc, 0, v33, vcc
	global_load_dwordx4 v[80:83], v[36:37], off offset:128
	global_load_dwordx4 v[84:87], v[38:39], off offset:128
	v_add_co_u32_e32 v36, vcc, s29, v32
	global_load_dwordx4 v[88:91], v[32:33], off offset:128
	global_load_dwordx4 v[92:95], v[34:35], off offset:128
	v_addc_co_u32_e32 v37, vcc, 0, v33, vcc
	v_add_co_u32_e32 v32, vcc, s34, v34
	s_cmp_lt_i32 s0, 4
	s_nop 0
	v_addc_co_u32_e32 v33, vcc, 0, v35, vcc
	global_load_dwordx4 v[96:99], v[36:37], off offset:128
	global_load_dwordx4 v[100:103], v[32:33], off offset:128
	v_add_co_u32_e32 v32, vcc, s35, v34
	s_cselect_b32 s47, 0, -1
	s_nop 0
	v_addc_co_u32_e32 v33, vcc, 0, v35, vcc
	v_add_co_u32_e32 v34, vcc, s38, v34
	s_cselect_b32 s46, 0, 0xfffffd00
	s_nop 0
	v_addc_co_u32_e32 v35, vcc, 0, v35, vcc
	global_load_dwordx4 v[124:127], v[32:33], off offset:128
	global_load_dwordx4 v[130:133], v[34:35], off offset:128
	s_waitcnt lgkmcnt(0)
	s_barrier
	s_waitcnt vmcnt(13)
	ds_write_b128 v64, v[8:11]
	ds_write_b128 v64, v[0:3] offset:4608
	ds_write_b128 v64, v[4:7] offset:9216
	s_waitcnt vmcnt(11)
	ds_write_b128 v64, v[16:19] offset:13824
	ds_write_b128 v64, v[12:15] offset:18432
	s_waitcnt vmcnt(10)
	ds_write_b128 v64, v[20:23] offset:23040
	s_waitcnt vmcnt(9)
	ds_write_b128 v64, v[24:27] offset:27648
	s_waitcnt vmcnt(8)
	ds_write_b128 v64, v[28:31] offset:32256
	v_lshl_add_u64 v[0:1], v[76:77], 0, s[46:47]
	v_add_co_u32_e32 v4, vcc, s21, v0
	s_waitcnt lgkmcnt(0)
	s_nop 0
	v_addc_co_u32_e32 v5, vcc, 0, v1, vcc
	v_add_co_u32_e32 v6, vcc, s28, v0
	s_barrier
	s_nop 0
	v_addc_co_u32_e32 v7, vcc, 0, v1, vcc
	global_load_dwordx4 v[134:137], v[4:5], off offset:256
	global_load_dwordx4 v[138:141], v[6:7], off offset:256
	v_add_co_u32_e32 v4, vcc, s29, v0
	v_lshl_add_u64 v[2:3], v[78:79], 0, s[46:47]
	s_nop 0
	v_addc_co_u32_e32 v5, vcc, 0, v1, vcc
	global_load_dwordx4 v[142:145], v[0:1], off offset:256
	global_load_dwordx4 v[146:149], v[2:3], off offset:256
	v_add_co_u32_e32 v0, vcc, s34, v2
	s_nop 1
	v_addc_co_u32_e32 v1, vcc, 0, v3, vcc
	global_load_dwordx4 v[150:153], v[4:5], off offset:256
	global_load_dwordx4 v[154:157], v[0:1], off offset:256
	v_add_co_u32_e32 v0, vcc, s35, v2
	s_nop 1
	v_addc_co_u32_e32 v1, vcc, 0, v3, vcc
	v_add_co_u32_e32 v2, vcc, s38, v2
	s_nop 1
	v_addc_co_u32_e32 v3, vcc, 0, v3, vcc
	global_load_dwordx4 v[162:165], v[0:1], off offset:256
	global_load_dwordx4 v[166:169], v[2:3], off offset:256
	v_and_b32_e32 v1, 31, v40
	v_lshrrev_b32_e32 v0, 1, v40
	v_and_or_b32 v2, v0, s40, v1
	v_and_b32_e32 v0, 16, v0
	v_mad_u64_u32 v[66:67], s[46:47], v2, s39, v[0:1]
	v_mad_u32_u24 v65, v1, s39, v0
	ds_read_b128 v[0:3], v66
	ds_read_b128 v[170:173], v66 offset:32
	ds_read_b128 v[4:7], v65 offset:18432
	ds_read_b128 v[174:177], v65 offset:18464
	ds_read_b128 v[8:11], v65 offset:23040
	ds_read_b128 v[178:181], v65 offset:23072
	ds_read_b128 v[12:15], v65 offset:27648
	ds_read_b128 v[182:185], v65 offset:27680
	ds_read_b128 v[186:189], v65 offset:32256
	ds_read_b128 v[190:193], v65 offset:32288
	ds_read_b128 v[194:197], v66 offset:64
	ds_read_b128 v[198:201], v66 offset:96
	ds_read_b128 v[202:205], v65 offset:18496
	ds_read_b128 v[206:209], v65 offset:18528
	ds_read_b128 v[210:213], v65 offset:23104
	ds_read_b128 v[214:217], v65 offset:23136
	ds_read_b128 v[218:221], v65 offset:27712
	ds_read_b128 v[222:225], v65 offset:27744
	ds_read_b128 v[226:229], v65 offset:32320
	ds_read_b128 v[230:233], v65 offset:32352
	s_setprio 2
	s_waitcnt lgkmcnt(14)
	v_mfma_f32_32x32x16_bf16 v[48:63], v[0:3], v[4:7], 0
	v_mfma_f32_32x32x16_bf16 v[32:47], v[0:3], v[8:11], 0
	s_waitcnt lgkmcnt(13)
	v_mfma_f32_32x32x16_bf16 v[16:31], v[0:3], v[12:15], 0
	s_waitcnt lgkmcnt(11)
	v_mfma_f32_32x32x16_bf16 v[0:15], v[0:3], v[186:189], 0
	v_mfma_f32_32x32x16_bf16 v[48:63], v[170:173], v[174:177], v[48:63]
	v_mfma_f32_32x32x16_bf16 v[32:47], v[170:173], v[178:181], v[32:47]
	v_mfma_f32_32x32x16_bf16 v[16:31], v[170:173], v[182:185], v[16:31]
	s_waitcnt lgkmcnt(10)
	v_mfma_f32_32x32x16_bf16 v[0:15], v[170:173], v[190:193], v[0:15]
	s_waitcnt lgkmcnt(7)
	v_mfma_f32_32x32x16_bf16 v[48:63], v[194:197], v[202:205], v[48:63]
	s_waitcnt lgkmcnt(5)
	v_mfma_f32_32x32x16_bf16 v[32:47], v[194:197], v[210:213], v[32:47]
	s_waitcnt lgkmcnt(3)
	v_mfma_f32_32x32x16_bf16 v[16:31], v[194:197], v[218:221], v[16:31]
	s_waitcnt lgkmcnt(1)
	v_mfma_f32_32x32x16_bf16 v[0:15], v[194:197], v[226:229], v[0:15]
	v_mfma_f32_32x32x16_bf16 v[48:63], v[198:201], v[206:209], v[48:63]
	v_mfma_f32_32x32x16_bf16 v[32:47], v[198:201], v[214:217], v[32:47]
	v_mfma_f32_32x32x16_bf16 v[16:31], v[198:201], v[222:225], v[16:31]
	s_waitcnt lgkmcnt(0)
	v_mfma_f32_32x32x16_bf16 v[0:15], v[198:201], v[230:233], v[0:15]
	s_setprio 0
	s_cmp_lt_i32 s0, 3
	s_cselect_b32 s47, 0, -1
	s_cselect_b32 s46, 0, 0xfffffd00
	s_barrier
; #define MFMA(a, b, c) __builtin_amdgcn_mfma_f32_32x32x16_bf16((a), (b), (c), 0, 0, 0)
; DI void gt_compute(const bf16* asr, const bf16* bsr, f32x16& acc0, f32x16& acc1, f32x16& acc2, f32x16& acc3) {
;   bf16x8 a[4], b0[4], b1[4], b2[4], b3[4];
; #pragma unroll
;   for (int kk = 0; kk < 4; ++kk) {
;     a[kk] = *(const bf16x8*)(asr + kk * 16);
;     b0[kk] = *(const bf16x8*)(bsr + kk * 16);
;     b1[kk] = *(const bf16x8*)(bsr + 32 * LDT + kk * 16);
;     b2[kk] = *(const bf16x8*)(bsr + 64 * LDT + kk * 16);
;     b3[kk] = *(const bf16x8*)(bsr + 96 * LDT + kk * 16);
;   }
;   __builtin_amdgcn_sched_barrier(0);
;   __builtin_amdgcn_s_setprio(2);
; #pragma unroll
;   for (int kk = 0; kk < 4; ++kk) {
;     acc0 = MFMA(a[kk], b0[kk], acc0); acc1 = MFMA(a[kk], b1[kk], acc1); acc2 = MFMA(a[kk], b2[kk], acc2); acc3 = MFMA(a[kk], b3[kk], acc3);
;   }
;   __builtin_amdgcn_s_setprio(0);
;   __builtin_amdgcn_sched_barrier(0);
; }
; DI void gemm_mainloop(const bf16* __restrict__ A, int lda, const bf16* __restrict__ Bt, int ldb, int K, int m0, int n0,
;                       bf16* As, bf16* Bs, f32x16& acc0, f32x16& acc1, f32x16& acc2, f32x16& acc3) {
;   const int tid = opaque_tid(), lane = tid & 63, w = tid >> 6, r = lane & 31, g = lane >> 5;
;   const int lrow = tid >> 3, lcc = (tid & 7) * 8;
;   const bf16* ap = A + (size_t)(m0 + lrow) * lda + lcc;
;   const bf16* bp = Bt + (size_t)(n0 + lrow) * ldb + lcc;
;   GTile t0, t1;
;   asm volatile("" ::: "memory");
;   const int nkt = K >> 6;
;   int kb = ((((m0 >> 7) * 5 + (n0 >> 7) * 3) >> 1) % nkt) << 6;
;     ...
;   gt_load(t0, ap, bp, lda, ldb, KW(0));
;   gt_load(t1, ap, bp, lda, ldb, KW(64));
; #pragma unroll
;   for (int i = 0; i < 16; ++i) { acc0[i] = 0.f; acc1[i] = 0.f; acc2[i] = 0.f; acc3[i] = 0.f; }
;   bf16* asw = As + lrow * LDT + lcc;
;   bf16* bsw = Bs + lrow * LDT + lcc;
;   const bf16* asr = As + (32 * w + r) * LDT + g * 8;
;   const bf16* bsr = Bs + r * LDT + g * 8;
;   for (int k0 = 0; k0 < K; k0 += 128) {
;     __syncthreads();
;     gt_store(t0, asw, bsw);
;     __syncthreads();
;     if (k0 + 128 < K) gt_load(t0, ap, bp, lda, ldb, KW(k0 + 128));
;     gt_compute(asr, bsr, acc0, acc1, acc2, acc3);
;     __syncthreads();
;     gt_store(t1, asw, bsw);
;     __syncthreads();
;     if (k0 + 192 < K) gt_load(t1, ap, bp, lda, ldb, KW(k0 + 192));
;     gt_compute(asr, bsr, acc0, acc1, acc2, acc3);
;   }
	s_waitcnt vmcnt(13)
	ds_write_b128 v64, v[88:91]
	ds_write_b128 v64, v[80:83] offset:4608
	ds_write_b128 v64, v[84:87] offset:9216
	s_waitcnt vmcnt(11)
	ds_write_b128 v64, v[96:99] offset:13824
	ds_write_b128 v64, v[92:95] offset:18432
	s_waitcnt vmcnt(10)
	ds_write_b128 v64, v[100:103] offset:23040
	s_waitcnt vmcnt(9)
	ds_write_b128 v64, v[124:127] offset:27648
	s_waitcnt vmcnt(8)
	ds_write_b128 v64, v[130:133] offset:32256
	v_lshl_add_u64 v[88:89], v[76:77], 0, s[46:47]
	v_add_co_u32_e32 v80, vcc, s21, v88
	v_lshl_add_u64 v[124:125], v[78:79], 0, s[46:47]
	s_nop 0
	v_addc_co_u32_e32 v81, vcc, 0, v89, vcc
	v_add_co_u32_e32 v84, vcc, s28, v88
	s_waitcnt lgkmcnt(0)
	s_nop 0
	v_addc_co_u32_e32 v85, vcc, 0, v89, vcc
	v_add_co_u32_e32 v96, vcc, s29, v88
	s_barrier
	s_nop 0
	v_addc_co_u32_e32 v97, vcc, 0, v89, vcc
	v_add_co_u32_e32 v100, vcc, s34, v124
	s_nop 1
	v_addc_co_u32_e32 v101, vcc, 0, v125, vcc
	v_add_co_u32_e32 v126, vcc, s35, v124
	global_load_dwordx4 v[80:83], v[80:81], off offset:384
	s_nop 0
	global_load_dwordx4 v[84:87], v[84:85], off offset:384
	v_addc_co_u32_e32 v127, vcc, 0, v125, vcc
	v_add_co_u32_e32 v128, vcc, s38, v124
	global_load_dwordx4 v[88:91], v[88:89], off offset:384
	s_nop 0
	global_load_dwordx4 v[92:95], v[124:125], off offset:384
	s_nop 0
	global_load_dwordx4 v[96:99], v[96:97], off offset:384
	s_nop 0
	global_load_dwordx4 v[100:103], v[100:101], off offset:384
	v_addc_co_u32_e32 v129, vcc, 0, v125, vcc
	global_load_dwordx4 v[124:127], v[126:127], off offset:384
	s_nop 0
	global_load_dwordx4 v[130:133], v[128:129], off offset:384
	ds_read_b128 v[170:173], v66
	ds_read_b128 v[174:177], v66 offset:32
	ds_read_b128 v[178:181], v65 offset:18432
	ds_read_b128 v[182:185], v65 offset:18464
	ds_read_b128 v[186:189], v65 offset:23040
	ds_read_b128 v[190:193], v65 offset:23072
	ds_read_b128 v[194:197], v65 offset:27648
	ds_read_b128 v[198:201], v65 offset:27680
	ds_read_b128 v[202:205], v65 offset:32256
	ds_read_b128 v[206:209], v65 offset:32288
	ds_read_b128 v[210:213], v66 offset:64
	ds_read_b128 v[214:217], v66 offset:96
	ds_read_b128 v[218:221], v65 offset:18496
	ds_read_b128 v[222:225], v65 offset:18528
	ds_read_b128 v[226:229], v65 offset:23104
	ds_read_b128 v[230:233], v65 offset:23136
	ds_read_b128 v[234:237], v65 offset:27712
	ds_read_b128 v[238:241], v65 offset:27744
	ds_read_b128 v[242:245], v65 offset:32320
	ds_read_b128 v[246:249], v65 offset:32352
	s_setprio 2
	s_waitcnt lgkmcnt(14)
	v_mfma_f32_32x32x16_bf16 v[48:63], v[170:173], v[178:181], v[48:63]
	v_mfma_f32_32x32x16_bf16 v[32:47], v[170:173], v[186:189], v[32:47]
	s_waitcnt lgkmcnt(13)
	v_mfma_f32_32x32x16_bf16 v[16:31], v[170:173], v[194:197], v[16:31]
	s_waitcnt lgkmcnt(11)
	v_mfma_f32_32x32x16_bf16 v[0:15], v[170:173], v[202:205], v[0:15]
	v_mfma_f32_32x32x16_bf16 v[48:63], v[174:177], v[182:185], v[48:63]
	v_mfma_f32_32x32x16_bf16 v[32:47], v[174:177], v[190:193], v[32:47]
	v_mfma_f32_32x32x16_bf16 v[16:31], v[174:177], v[198:201], v[16:31]
	s_waitcnt lgkmcnt(10)
	v_mfma_f32_32x32x16_bf16 v[0:15], v[174:177], v[206:209], v[0:15]
	s_waitcnt lgkmcnt(7)
	v_mfma_f32_32x32x16_bf16 v[48:63], v[210:213], v[218:221], v[48:63]
	s_waitcnt lgkmcnt(5)
	v_mfma_f32_32x32x16_bf16 v[32:47], v[210:213], v[226:229], v[32:47]
	s_waitcnt lgkmcnt(3)
	v_mfma_f32_32x32x16_bf16 v[16:31], v[210:213], v[234:237], v[16:31]
	s_waitcnt lgkmcnt(1)
	v_mfma_f32_32x32x16_bf16 v[0:15], v[210:213], v[242:245], v[0:15]
	v_mfma_f32_32x32x16_bf16 v[48:63], v[214:217], v[222:225], v[48:63]
	v_mfma_f32_32x32x16_bf16 v[32:47], v[214:217], v[230:233], v[32:47]
	v_mfma_f32_32x32x16_bf16 v[16:31], v[214:217], v[238:241], v[16:31]
	s_waitcnt lgkmcnt(0)
	v_mfma_f32_32x32x16_bf16 v[0:15], v[214:217], v[246:249], v[0:15]
	s_setprio 0
	s_cmp_lt_i32 s0, 2
	s_cselect_b32 s47, 0, -1
	s_cselect_b32 s46, 0, 0xfffffd00
	v_lshl_add_u64 v[128:129], v[76:77], 0, s[46:47]
	s_barrier
	s_waitcnt vmcnt(13)
	ds_write_b128 v64, v[142:145]
	ds_write_b128 v64, v[134:137] offset:4608
	ds_write_b128 v64, v[138:141] offset:9216
	s_waitcnt vmcnt(11)
	ds_write_b128 v64, v[150:153] offset:13824
	ds_write_b128 v64, v[146:149] offset:18432
	s_waitcnt vmcnt(10)
	ds_write_b128 v64, v[154:157] offset:23040
	s_waitcnt vmcnt(9)
	ds_write_b128 v64, v[162:165] offset:27648
	s_waitcnt vmcnt(8)
	ds_write_b128 v64, v[166:169] offset:32256
	v_add_co_u32_e32 v134, vcc, s21, v128
	v_lshl_add_u64 v[162:163], v[78:79], 0, s[46:47]
	s_nop 0
	v_addc_co_u32_e32 v135, vcc, 0, v129, vcc
	v_add_co_u32_e32 v138, vcc, s28, v128
	s_waitcnt lgkmcnt(0)
	s_nop 0
	v_addc_co_u32_e32 v139, vcc, 0, v129, vcc
	v_add_co_u32_e32 v150, vcc, s29, v128
	s_barrier
; #define MFMA(a, b, c) __builtin_amdgcn_mfma_f32_32x32x16_bf16((a), (b), (c), 0, 0, 0)
; DI void gt_compute(const bf16* asr, const bf16* bsr, f32x16& acc0, f32x16& acc1, f32x16& acc2, f32x16& acc3) {
;   bf16x8 a[4], b0[4], b1[4], b2[4], b3[4];
; #pragma unroll
;   for (int kk = 0; kk < 4; ++kk) {
;     a[kk] = *(const bf16x8*)(asr + kk * 16);
;     b0[kk] = *(const bf16x8*)(bsr + kk * 16);
;     b1[kk] = *(const bf16x8*)(bsr + 32 * LDT + kk * 16);
;     b2[kk] = *(const bf16x8*)(bsr + 64 * LDT + kk * 16);
;     b3[kk] = *(const bf16x8*)(bsr + 96 * LDT + kk * 16);
;   }
;   __builtin_amdgcn_sched_barrier(0);
;   __builtin_amdgcn_s_setprio(2);
; #pragma unroll
;   for (int kk = 0; kk < 4; ++kk) {
;     acc0 = MFMA(a[kk], b0[kk], acc0); acc1 = MFMA(a[kk], b1[kk], acc1); acc2 = MFMA(a[kk], b2[kk], acc2); acc3 = MFMA(a[kk], b3[kk], acc3);
;   }
;   __builtin_amdgcn_s_setprio(0);
;   __builtin_amdgcn_sched_barrier(0);
; }
; DI void gemm_mainloop(const bf16* __restrict__ A, int lda, const bf16* __restrict__ Bt, int ldb, int K, int m0, int n0,
;                       bf16* As, bf16* Bs, f32x16& acc0, f32x16& acc1, f32x16& acc2, f32x16& acc3) {
;   const int tid = opaque_tid(), lane = tid & 63, w = tid >> 6, r = lane & 31, g = lane >> 5;
;   const int lrow = tid >> 3, lcc = (tid & 7) * 8;
;   const bf16* ap = A + (size_t)(m0 + lrow) * lda + lcc;
;   const bf16* bp = Bt + (size_t)(n0 + lrow) * ldb + lcc;
;   GTile t0, t1;
;   asm volatile("" ::: "memory");
;   const int nkt = K >> 6;
;   int kb = ((((m0 >> 7) * 5 + (n0 >> 7) * 3) >> 1) % nkt) << 6;
;     ...
;   gt_load(t0, ap, bp, lda, ldb, KW(0));
;   gt_load(t1, ap, bp, lda, ldb, KW(64));
; #pragma unroll
;   for (int i = 0; i < 16; ++i) { acc0[i] = 0.f; acc1[i] = 0.f; acc2[i] = 0.f; acc3[i] = 0.f; }
;   bf16* asw = As + lrow * LDT + lcc;
;   bf16* bsw = Bs + lrow * LDT + lcc;
;   const bf16* asr = As + (32 * w + r) * LDT + g * 8;
;   const bf16* bsr = Bs + r * LDT + g * 8;
;   for (int k0 = 0; k0 < K; k0 += 128) {
;     __syncthreads();
;     gt_store(t0, asw, bsw);
;     __syncthreads();
;     if (k0 + 128 < K) gt_load(t0, ap, bp, lda, ldb, KW(k0 + 128));
;     gt_compute(asr, bsr, acc0, acc1, acc2, acc3);
;     __syncthreads();
;     gt_store(t1, asw, bsw);
;     __syncthreads();
;     if (k0 + 192 < K) gt_load(t1, ap, bp, lda, ldb, KW(k0 + 192));
;     gt_compute(asr, bsr, acc0, acc1, acc2, acc3);
;   }
	s_nop 0
	v_addc_co_u32_e32 v151, vcc, 0, v129, vcc
	global_load_dwordx4 v[134:137], v[134:135], off offset:512
	s_nop 0
	global_load_dwordx4 v[138:141], v[138:139], off offset:512
	s_nop 0
	global_load_dwordx4 v[142:145], v[128:129], off offset:512
	global_load_dwordx4 v[146:149], v[162:163], off offset:512
	v_add_co_u32_e32 v128, vcc, s34, v162
	s_nop 1
	v_addc_co_u32_e32 v129, vcc, 0, v163, vcc
	global_load_dwordx4 v[150:153], v[150:151], off offset:512
	s_nop 0
	global_load_dwordx4 v[154:157], v[128:129], off offset:512
	v_add_co_u32_e32 v128, vcc, s35, v162
	s_nop 1
	v_addc_co_u32_e32 v129, vcc, 0, v163, vcc
	v_add_co_u32_e32 v166, vcc, s38, v162
	s_nop 1
	v_addc_co_u32_e32 v167, vcc, 0, v163, vcc
	global_load_dwordx4 v[162:165], v[128:129], off offset:512
	s_nop 0
	global_load_dwordx4 v[166:169], v[166:167], off offset:512
	ds_read_b128 v[170:173], v66
	ds_read_b128 v[174:177], v66 offset:32
	ds_read_b128 v[178:181], v65 offset:18432
	ds_read_b128 v[182:185], v65 offset:18464
	ds_read_b128 v[186:189], v65 offset:23040
	ds_read_b128 v[190:193], v65 offset:23072
	ds_read_b128 v[194:197], v65 offset:27648
	ds_read_b128 v[198:201], v65 offset:27680
	ds_read_b128 v[202:205], v65 offset:32256
	ds_read_b128 v[206:209], v65 offset:32288
	ds_read_b128 v[210:213], v66 offset:64
	ds_read_b128 v[214:217], v66 offset:96
	ds_read_b128 v[218:221], v65 offset:18496
	ds_read_b128 v[222:225], v65 offset:18528
	ds_read_b128 v[226:229], v65 offset:23104
	ds_read_b128 v[230:233], v65 offset:23136
	ds_read_b128 v[234:237], v65 offset:27712
	ds_read_b128 v[238:241], v65 offset:27744
	ds_read_b128 v[242:245], v65 offset:32320
	ds_read_b128 v[246:249], v65 offset:32352
	s_setprio 2
	s_waitcnt lgkmcnt(14)
	v_mfma_f32_32x32x16_bf16 v[48:63], v[170:173], v[178:181], v[48:63]
	v_mfma_f32_32x32x16_bf16 v[32:47], v[170:173], v[186:189], v[32:47]
	s_waitcnt lgkmcnt(13)
	v_mfma_f32_32x32x16_bf16 v[16:31], v[170:173], v[194:197], v[16:31]
	s_waitcnt lgkmcnt(11)
	v_mfma_f32_32x32x16_bf16 v[0:15], v[170:173], v[202:205], v[0:15]
	v_mfma_f32_32x32x16_bf16 v[48:63], v[174:177], v[182:185], v[48:63]
	v_mfma_f32_32x32x16_bf16 v[32:47], v[174:177], v[190:193], v[32:47]
	v_mfma_f32_32x32x16_bf16 v[16:31], v[174:177], v[198:201], v[16:31]
	s_waitcnt lgkmcnt(10)
	v_mfma_f32_32x32x16_bf16 v[0:15], v[174:177], v[206:209], v[0:15]
	s_waitcnt lgkmcnt(7)
	v_mfma_f32_32x32x16_bf16 v[48:63], v[210:213], v[218:221], v[48:63]
	s_waitcnt lgkmcnt(5)
	v_mfma_f32_32x32x16_bf16 v[32:47], v[210:213], v[226:229], v[32:47]
	s_waitcnt lgkmcnt(3)
	v_mfma_f32_32x32x16_bf16 v[16:31], v[210:213], v[234:237], v[16:31]
	s_waitcnt lgkmcnt(1)
	v_mfma_f32_32x32x16_bf16 v[0:15], v[210:213], v[242:245], v[0:15]
	v_mfma_f32_32x32x16_bf16 v[48:63], v[214:217], v[222:225], v[48:63]
	v_mfma_f32_32x32x16_bf16 v[32:47], v[214:217], v[230:233], v[32:47]
	v_mfma_f32_32x32x16_bf16 v[16:31], v[214:217], v[238:241], v[16:31]
	s_waitcnt lgkmcnt(0)
	v_mfma_f32_32x32x16_bf16 v[0:15], v[214:217], v[246:249], v[0:15]
	s_setprio 0
	s_cmp_gt_i32 s0, 0
	s_cselect_b32 s1, -1, 0
	s_cselect_b32 s0, 0xfffffd00, 0
	s_barrier
	s_waitcnt vmcnt(13)
	ds_write_b128 v64, v[88:91]
	ds_write_b128 v64, v[80:83] offset:4608
	ds_write_b128 v64, v[84:87] offset:9216
	s_waitcnt vmcnt(11)
	ds_write_b128 v64, v[96:99] offset:13824
	ds_write_b128 v64, v[92:95] offset:18432
	s_waitcnt vmcnt(10)
	ds_write_b128 v64, v[100:103] offset:23040
	s_waitcnt vmcnt(9)
	ds_write_b128 v64, v[124:127] offset:27648
	s_waitcnt vmcnt(8)
	ds_write_b128 v64, v[130:133] offset:32256
	v_lshl_add_u64 v[84:85], v[76:77], 0, s[0:1]
	v_add_co_u32_e32 v76, vcc, s21, v84
	v_lshl_add_u64 v[100:101], v[78:79], 0, s[0:1]
	s_nop 0
	v_addc_co_u32_e32 v77, vcc, 0, v85, vcc
	v_add_co_u32_e32 v80, vcc, s28, v84
	s_waitcnt lgkmcnt(0)
	s_nop 0
	v_addc_co_u32_e32 v81, vcc, 0, v85, vcc
	v_add_co_u32_e32 v92, vcc, s29, v84
	s_barrier
	s_nop 0
	v_addc_co_u32_e32 v93, vcc, 0, v85, vcc
	v_add_co_u32_e32 v96, vcc, s34, v100
	s_nop 1
	v_addc_co_u32_e32 v97, vcc, 0, v101, vcc
	v_add_co_u32_e32 v102, vcc, s35, v100
	global_load_dwordx4 v[76:79], v[76:77], off offset:640
	s_nop 0
	global_load_dwordx4 v[80:83], v[80:81], off offset:640
	v_addc_co_u32_e32 v103, vcc, 0, v101, vcc
	v_add_co_u32_e32 v124, vcc, s38, v100
	global_load_dwordx4 v[84:87], v[84:85], off offset:640
	s_nop 0
	global_load_dwordx4 v[88:91], v[100:101], off offset:640
	v_addc_co_u32_e32 v125, vcc, 0, v101, vcc
	global_load_dwordx4 v[92:95], v[92:93], off offset:640
	s_nop 0
	global_load_dwordx4 v[96:99], v[96:97], off offset:640
	s_nop 0
	global_load_dwordx4 v[100:103], v[102:103], off offset:640
	s_nop 0
	global_load_dwordx4 v[124:127], v[124:125], off offset:640
	ds_read_b128 v[130:133], v66
	ds_read_b128 v[170:173], v66 offset:32
	ds_read_b128 v[174:177], v65 offset:18432
	ds_read_b128 v[178:181], v65 offset:18464
	ds_read_b128 v[182:185], v65 offset:23040
	ds_read_b128 v[186:189], v65 offset:23072
	ds_read_b128 v[190:193], v65 offset:27648
	ds_read_b128 v[194:197], v65 offset:27680
	ds_read_b128 v[198:201], v65 offset:32256
	ds_read_b128 v[202:205], v65 offset:32288
	ds_read_b128 v[206:209], v66 offset:64
	ds_read_b128 v[210:213], v66 offset:96
	ds_read_b128 v[214:217], v65 offset:18496
	ds_read_b128 v[218:221], v65 offset:18528
	ds_read_b128 v[222:225], v65 offset:23104
	ds_read_b128 v[226:229], v65 offset:23136
	ds_read_b128 v[230:233], v65 offset:27712
	ds_read_b128 v[234:237], v65 offset:27744
	ds_read_b128 v[238:241], v65 offset:32320
	ds_read_b128 v[242:245], v65 offset:32352
	s_setprio 2
	s_waitcnt lgkmcnt(14)
	v_mfma_f32_32x32x16_bf16 v[48:63], v[130:133], v[174:177], v[48:63]
	v_mfma_f32_32x32x16_bf16 v[32:47], v[130:133], v[182:185], v[32:47]
	s_waitcnt lgkmcnt(13)
	v_mfma_f32_32x32x16_bf16 v[16:31], v[130:133], v[190:193], v[16:31]
	s_waitcnt lgkmcnt(11)
	v_mfma_f32_32x32x16_bf16 v[0:15], v[130:133], v[198:201], v[0:15]
	v_mfma_f32_32x32x16_bf16 v[48:63], v[170:173], v[178:181], v[48:63]
	v_mfma_f32_32x32x16_bf16 v[32:47], v[170:173], v[186:189], v[32:47]
	v_mfma_f32_32x32x16_bf16 v[16:31], v[170:173], v[194:197], v[16:31]
	s_waitcnt lgkmcnt(10)
	v_mfma_f32_32x32x16_bf16 v[0:15], v[170:173], v[202:205], v[0:15]
	s_waitcnt lgkmcnt(7)
	v_mfma_f32_32x32x16_bf16 v[48:63], v[206:209], v[214:217], v[48:63]
	s_waitcnt lgkmcnt(5)
	v_mfma_f32_32x32x16_bf16 v[32:47], v[206:209], v[222:225], v[32:47]
	s_waitcnt lgkmcnt(3)
	v_mfma_f32_32x32x16_bf16 v[16:31], v[206:209], v[230:233], v[16:31]
	s_waitcnt lgkmcnt(1)
	v_mfma_f32_32x32x16_bf16 v[0:15], v[206:209], v[238:241], v[0:15]
	v_mfma_f32_32x32x16_bf16 v[48:63], v[210:213], v[218:221], v[48:63]
	v_mfma_f32_32x32x16_bf16 v[32:47], v[210:213], v[226:229], v[32:47]
	v_mfma_f32_32x32x16_bf16 v[16:31], v[210:213], v[234:237], v[16:31]
	s_waitcnt lgkmcnt(0)
	v_mfma_f32_32x32x16_bf16 v[0:15], v[210:213], v[242:245], v[0:15]
	s_setprio 0
	s_barrier
; DI bf16 f2bf(float a) { return (bf16)(pack2(a, 0.f) & 0xffffu); }
; DI int crow(int i, int g) { return (i & 3) + 8 * (i >> 2) + 4 * g; }
; DI void gemm_mainloop(const bf16* __restrict__ A, int lda, const bf16* __restrict__ Bt, int ldb, int K, int m0, int n0,
;                       bf16* As, bf16* Bs, f32x16& acc0, f32x16& acc1, f32x16& acc2, f32x16& acc3) {
;     ...
;   for (int k0 = 0; k0 < K; k0 += 128) {
;     __syncthreads();
;     gt_store(t0, asw, bsw);
;     __syncthreads();
;     if (k0 + 128 < K) gt_load(t0, ap, bp, lda, ldb, KW(k0 + 128));
;     gt_compute(asr, bsr, acc0, acc1, acc2, acc3);
;     __syncthreads();
;     gt_store(t1, asw, bsw);
;     __syncthreads();
;     if (k0 + 192 < K) gt_load(t1, ap, bp, lda, ldb, KW(k0 + 192));
;     gt_compute(asr, bsr, acc0, acc1, acc2, acc3);
;     ...
;       for (int j = 0; j < 4; ++j) {
;         const int n = n0 + 32 * j;
;         const int hh = n / 192, d0 = n % 192;
;         if (d0 < 128) {
; #pragma unroll
;           for (int i = 0; i < 16; ++i) {
;             int rl = 32 * w + crow(i, g);
;             int s = (m0 & 2047) + rl;
;             Qb[((size_t)(bidx * 8 + hh) * 2048 + s) * 192 + d0 + r] = f2bf(acc[j][i] * rs[rl]);
;           }
;         } else if (d0 == 128) {
;           if (j < 3) {
	s_waitcnt vmcnt(13)
	ds_write_b128 v64, v[142:145]
	ds_write_b128 v64, v[134:137] offset:4608
	ds_write_b128 v64, v[138:141] offset:9216
	s_waitcnt vmcnt(11)
	ds_write_b128 v64, v[150:153] offset:13824
	ds_write_b128 v64, v[146:149] offset:18432
	s_waitcnt vmcnt(10)
	ds_write_b128 v64, v[154:157] offset:23040
	s_waitcnt vmcnt(9)
	ds_write_b128 v64, v[162:165] offset:27648
	s_waitcnt vmcnt(8)
	ds_write_b128 v64, v[166:169] offset:32256
	s_waitcnt lgkmcnt(0)
	s_barrier
	ds_read_b128 v[130:133], v66
	ds_read_b128 v[134:137], v66 offset:32
	ds_read_b128 v[138:141], v65 offset:18432
	ds_read_b128 v[142:145], v65 offset:18464
	ds_read_b128 v[146:149], v65 offset:23040
	ds_read_b128 v[150:153], v65 offset:23072
	ds_read_b128 v[154:157], v65 offset:27648
	ds_read_b128 v[162:165], v65 offset:27680
	ds_read_b128 v[166:169], v65 offset:32256
	ds_read_b128 v[170:173], v65 offset:32288
	ds_read_b128 v[174:177], v66 offset:64
	ds_read_b128 v[178:181], v66 offset:96
	ds_read_b128 v[182:185], v65 offset:18496
	ds_read_b128 v[186:189], v65 offset:18528
	ds_read_b128 v[190:193], v65 offset:23104
	ds_read_b128 v[194:197], v65 offset:23136
	ds_read_b128 v[198:201], v65 offset:27712
	ds_read_b128 v[202:205], v65 offset:27744
	ds_read_b128 v[206:209], v65 offset:32320
	ds_read_b128 v[210:213], v65 offset:32352
	s_setprio 2
	s_waitcnt lgkmcnt(14)
	v_mfma_f32_32x32x16_bf16 v[48:63], v[130:133], v[138:141], v[48:63]
	v_mfma_f32_32x32x16_bf16 v[32:47], v[130:133], v[146:149], v[32:47]
	s_waitcnt lgkmcnt(13)
	v_mfma_f32_32x32x16_bf16 v[16:31], v[130:133], v[154:157], v[16:31]
	s_waitcnt lgkmcnt(11)
	v_mfma_f32_32x32x16_bf16 v[0:15], v[130:133], v[166:169], v[0:15]
	v_mfma_f32_32x32x16_bf16 v[48:63], v[134:137], v[142:145], v[48:63]
	v_mfma_f32_32x32x16_bf16 v[32:47], v[134:137], v[150:153], v[32:47]
	v_mfma_f32_32x32x16_bf16 v[16:31], v[134:137], v[162:165], v[16:31]
	s_waitcnt lgkmcnt(10)
	v_mfma_f32_32x32x16_bf16 v[0:15], v[134:137], v[170:173], v[0:15]
	s_waitcnt lgkmcnt(7)
	v_mfma_f32_32x32x16_bf16 v[48:63], v[174:177], v[182:185], v[48:63]
	s_waitcnt lgkmcnt(5)
	v_mfma_f32_32x32x16_bf16 v[32:47], v[174:177], v[190:193], v[32:47]
	s_waitcnt lgkmcnt(3)
	v_mfma_f32_32x32x16_bf16 v[16:31], v[174:177], v[198:201], v[16:31]
	s_waitcnt lgkmcnt(1)
	v_mfma_f32_32x32x16_bf16 v[0:15], v[174:177], v[206:209], v[0:15]
	v_mfma_f32_32x32x16_bf16 v[48:63], v[178:181], v[186:189], v[48:63]
	v_mfma_f32_32x32x16_bf16 v[32:47], v[178:181], v[194:197], v[32:47]
	v_mfma_f32_32x32x16_bf16 v[16:31], v[178:181], v[202:205], v[16:31]
	s_waitcnt lgkmcnt(0)
	v_mfma_f32_32x32x16_bf16 v[0:15], v[178:181], v[210:213], v[0:15]
	s_setprio 0
	s_barrier
	s_waitcnt vmcnt(5)
	ds_write_b128 v64, v[84:87]
	ds_write_b128 v64, v[76:79] offset:4608
	ds_write_b128 v64, v[80:83] offset:9216
	s_waitcnt vmcnt(3)
	ds_write_b128 v64, v[92:95] offset:13824
	ds_write_b128 v64, v[88:91] offset:18432
	s_waitcnt vmcnt(2)
	ds_write_b128 v64, v[96:99] offset:23040
	s_waitcnt vmcnt(1)
	ds_write_b128 v64, v[100:103] offset:27648
	s_waitcnt vmcnt(0)
	ds_write_b128 v64, v[124:127] offset:32256
	s_waitcnt lgkmcnt(0)
	s_barrier
	ds_read_b128 v[76:79], v66
	ds_read_b128 v[80:83], v66 offset:32
	ds_read_b128 v[84:87], v65 offset:18432
	ds_read_b128 v[88:91], v65 offset:18464
	ds_read_b128 v[92:95], v65 offset:23040
	ds_read_b128 v[96:99], v65 offset:23072
	ds_read_b128 v[100:103], v65 offset:27648
	ds_read_b128 v[124:127], v65 offset:27680
	ds_read_b128 v[130:133], v65 offset:32256
	ds_read_b128 v[134:137], v65 offset:32288
	ds_read_b128 v[138:141], v66 offset:64
	ds_read_b128 v[142:145], v66 offset:96
	ds_read_b128 v[146:149], v65 offset:18496
	ds_read_b128 v[150:153], v65 offset:18528
	ds_read_b128 v[154:157], v65 offset:23104
	ds_read_b128 v[162:165], v65 offset:23136
	ds_read_b128 v[166:169], v65 offset:27712
	ds_read_b128 v[170:173], v65 offset:27744
	ds_read_b128 v[174:177], v65 offset:32320
	ds_read_b128 v[64:67], v65 offset:32352
	s_setprio 2
	s_waitcnt lgkmcnt(14)
	v_mfma_f32_32x32x16_bf16 v[48:63], v[76:79], v[84:87], v[48:63]
	v_mfma_f32_32x32x16_bf16 v[32:47], v[76:79], v[92:95], v[32:47]
	s_waitcnt lgkmcnt(13)
	v_mfma_f32_32x32x16_bf16 v[16:31], v[76:79], v[100:103], v[16:31]
	s_waitcnt lgkmcnt(11)
	v_mfma_f32_32x32x16_bf16 v[0:15], v[76:79], v[130:133], v[0:15]
	v_mfma_f32_32x32x16_bf16 v[48:63], v[80:83], v[88:91], v[48:63]
	v_mfma_f32_32x32x16_bf16 v[32:47], v[80:83], v[96:99], v[32:47]
	v_mfma_f32_32x32x16_bf16 v[16:31], v[80:83], v[124:127], v[16:31]
	s_waitcnt lgkmcnt(10)
	v_mfma_f32_32x32x16_bf16 v[0:15], v[80:83], v[134:137], v[0:15]
	s_waitcnt lgkmcnt(7)
	v_mfma_f32_32x32x16_bf16 v[48:63], v[138:141], v[146:149], v[48:63]
	s_waitcnt lgkmcnt(5)
	v_mfma_f32_32x32x16_bf16 v[32:47], v[138:141], v[154:157], v[32:47]
	s_waitcnt lgkmcnt(3)
	v_mfma_f32_32x32x16_bf16 v[16:31], v[138:141], v[166:169], v[16:31]
	s_waitcnt lgkmcnt(1)
	v_mfma_f32_32x32x16_bf16 v[0:15], v[138:141], v[174:177], v[0:15]
	v_mfma_f32_32x32x16_bf16 v[48:63], v[142:145], v[150:153], v[48:63]
	v_mfma_f32_32x32x16_bf16 v[32:47], v[142:145], v[162:165], v[32:47]
	v_mfma_f32_32x32x16_bf16 v[16:31], v[142:145], v[170:173], v[16:31]
	s_waitcnt lgkmcnt(0)
	v_mfma_f32_32x32x16_bf16 v[0:15], v[142:145], v[64:67], v[0:15]
	s_setprio 0
	s_ashr_i32 s0, s14, 1
	s_and_b32 s45, s0, -8
	s_mul_i32 s0, s12, 0x2aab
	s_lshr_b32 s1, s0, 31
	s_ashr_i32 s13, s0, 21
	s_add_i32 s13, s13, s1
	s_mul_i32 s0, s13, 0xc0
	s_sub_i32 s0, s12, s0
	s_and_b32 s46, s15, 0x780
	s_sext_i32_i16 s12, s0
	s_cmpk_gt_i32 s12, 0x7f
	s_mov_b64 s[14:15], -1
	s_barrier
	s_cbranch_scc0 .LBB0_329
	s_and_b32 s0, 0xffff, s0
	s_cmpk_lg_i32 s0, 0x80
	s_cbranch_scc1 .LBB0_328
; DI bf16 f2bf(float a) { return (bf16)(pack2(a, 0.f) & 0xffffu); }
; DI int crow(int i, int g) { return (i & 3) + 8 * (i >> 2) + 4 * g; }
;     ...
;         } else if (d0 == 128) {
;           if (j < 3) {
; #pragma unroll
;             for (int i = 0; i < 16; ++i) {
;               int rl = 32 * w + crow(i, g);
;               int s = (m0 & 2047) + rl;
;               float2 cs = t64[s * 32 + r];
;               float x1 = acc[j][i] * rs[rl], x2 = acc[(j + 1) & 3][i] * rs[rl];
;               bf16* qp = Qb + ((size_t)(bidx * 8 + hh) * 2048 + s) * 192 + 128;
;               qp[r] = f2bf(x1 * cs.x - x2 * cs.y);
;               qp[32 + r] = f2bf(x2 * cs.x + x1 * cs.y);
;             }
;           }
	v_add_u32_e32 v80, s46, v107
	v_lshl_or_b32 v64, v80, 5, v105
	v_ashrrev_i32_e32 v65, 31, v64
	v_lshl_add_u64 v[64:65], v[64:65], 3, s[10:11]
	global_load_dwordx2 v[82:83], v[64:65], off
	v_add_u32_e32 v232, s46, v109
	v_lshl_or_b32 v232, v232, 5, v105
	v_mov_b32_e32 v233, 0
	v_lshl_add_u64 v[232:233], v[232:233], 3, s[10:11]
	global_load_dwordx2 v[202:203], v[232:233], off
	v_add_u32_e32 v234, s46, v110
	v_lshl_or_b32 v234, v234, 5, v105
	v_mov_b32_e32 v235, 0
	v_lshl_add_u64 v[234:235], v[234:235], 3, s[10:11]
	global_load_dwordx2 v[204:205], v[234:235], off
	v_add_u32_e32 v232, s46, v111
	v_lshl_or_b32 v232, v232, 5, v105
	v_mov_b32_e32 v233, 0
	v_lshl_add_u64 v[232:233], v[232:233], 3, s[10:11]
	global_load_dwordx2 v[206:207], v[232:233], off
	v_add_u32_e32 v234, s46, v112
	v_lshl_or_b32 v234, v234, 5, v105
	v_mov_b32_e32 v235, 0
	v_lshl_add_u64 v[234:235], v[234:235], 3, s[10:11]
	global_load_dwordx2 v[208:209], v[234:235], off
	v_add_u32_e32 v232, s46, v113
	v_lshl_or_b32 v232, v232, 5, v105
	v_mov_b32_e32 v233, 0
	v_lshl_add_u64 v[232:233], v[232:233], 3, s[10:11]
	global_load_dwordx2 v[210:211], v[232:233], off
	v_add_u32_e32 v234, s46, v114
	v_lshl_or_b32 v234, v234, 5, v105
	v_mov_b32_e32 v235, 0
	v_lshl_add_u64 v[234:235], v[234:235], 3, s[10:11]
	global_load_dwordx2 v[212:213], v[234:235], off
	v_add_u32_e32 v232, s46, v115
	v_lshl_or_b32 v232, v232, 5, v105
	v_mov_b32_e32 v233, 0
	v_lshl_add_u64 v[232:233], v[232:233], 3, s[10:11]
	global_load_dwordx2 v[214:215], v[232:233], off
	v_add_u32_e32 v234, s46, v116
	v_lshl_or_b32 v234, v234, 5, v105
	v_mov_b32_e32 v235, 0
	v_lshl_add_u64 v[234:235], v[234:235], 3, s[10:11]
	global_load_dwordx2 v[216:217], v[234:235], off
	v_add_u32_e32 v232, s46, v117
	v_lshl_or_b32 v232, v232, 5, v105
	v_mov_b32_e32 v233, 0
	v_lshl_add_u64 v[232:233], v[232:233], 3, s[10:11]
	global_load_dwordx2 v[218:219], v[232:233], off
	v_add_u32_e32 v234, s46, v118
	v_lshl_or_b32 v234, v234, 5, v105
	v_mov_b32_e32 v235, 0
	v_lshl_add_u64 v[234:235], v[234:235], 3, s[10:11]
	global_load_dwordx2 v[220:221], v[234:235], off
	v_add_u32_e32 v232, s46, v119
	v_lshl_or_b32 v232, v232, 5, v105
	v_mov_b32_e32 v233, 0
	v_lshl_add_u64 v[232:233], v[232:233], 3, s[10:11]
	global_load_dwordx2 v[222:223], v[232:233], off
	v_add_u32_e32 v234, s46, v120
	v_lshl_or_b32 v234, v234, 5, v105
	v_mov_b32_e32 v235, 0
	v_lshl_add_u64 v[234:235], v[234:235], 3, s[10:11]
	global_load_dwordx2 v[224:225], v[234:235], off
	v_add_u32_e32 v232, s46, v121
	v_lshl_or_b32 v232, v232, 5, v105
	v_mov_b32_e32 v233, 0
	v_lshl_add_u64 v[232:233], v[232:233], 3, s[10:11]
	global_load_dwordx2 v[226:227], v[232:233], off
	v_add_u32_e32 v234, s46, v122
	v_lshl_or_b32 v234, v234, 5, v105
	v_mov_b32_e32 v235, 0
	v_lshl_add_u64 v[234:235], v[234:235], 3, s[10:11]
	global_load_dwordx2 v[228:229], v[234:235], off
	v_add_u32_e32 v232, s46, v123
	v_lshl_or_b32 v232, v232, 5, v105
	v_mov_b32_e32 v233, 0
	v_lshl_add_u64 v[232:233], v[232:233], 3, s[10:11]
	global_load_dwordx2 v[230:231], v[232:233], off
	ds_read_b128 v[76:79], v108 offset:40960
	ds_read_b128 v[64:67], v108 offset:40992
	s_add_i32 s0, s45, s13
	s_ashr_i32 s1, s0, 31
	v_ashrrev_i32_e32 v81, 31, v80
	s_lshl_b64 s[14:15], s[0:1], 11
	v_lshl_add_u64 v[80:81], s[14:15], 0, v[80:81]
	s_waitcnt lgkmcnt(1)
	v_mul_f32_e32 v68, v48, v76
	v_mul_f32_e32 v76, v32, v76
	v_add_u32_e32 v84, s46, v109
	v_mad_u64_u32 v[88:89], s[0:1], v80, s41, v[70:71]
	v_lshl_or_b32 v86, v84, 5, v105
	v_ashrrev_i32_e32 v87, 31, v86
	v_mad_i32_i24 v89, v81, s41, v89
	v_lshl_add_u64 v[86:87], v[86:87], 3, s[10:11]
	v_ashrrev_i32_e32 v85, 31, v84
	v_lshl_add_u64 v[84:85], s[14:15], 0, v[84:85]
	s_waitcnt vmcnt(0)
	v_mul_f32_e32 v80, v83, v76
	v_mul_f32_e32 v76, v82, v76
	v_fma_f32 v80, v82, v68, -v80
	v_fmac_f32_e32 v76, v83, v68
	v_cvt_pk_bf16_f32 v68, v80, s0
	v_cvt_pk_bf16_f32 v76, v76, s0
	global_store_short v[88:89], v68, off offset:256
	global_store_short v[88:89], v76, off offset:320
	v_mov_b32_e32 v80, v202
	v_mov_b32_e32 v81, v203
	v_mul_f32_e32 v68, v49, v77
	v_mul_f32_e32 v77, v33, v77
	v_add_u32_e32 v76, s46, v110
	v_mad_u64_u32 v[86:87], s[0:1], v84, s41, v[70:71]
	v_lshl_or_b32 v82, v76, 5, v105
	v_ashrrev_i32_e32 v83, 31, v82
	v_mad_i32_i24 v87, v85, s41, v87
	v_lshl_add_u64 v[82:83], v[82:83], 3, s[10:11]
	v_mul_f32_e32 v84, v81, v77
	v_mul_f32_e32 v77, v80, v77
	v_fma_f32 v80, v80, v68, -v84
	v_fmac_f32_e32 v77, v81, v68
	v_cvt_pk_bf16_f32 v68, v80, s0
	v_cvt_pk_bf16_f32 v77, v77, s0
	global_store_short v[86:87], v68, off offset:256
	global_store_short v[86:87], v77, off offset:320
	v_mov_b32_e32 v80, v204
	v_mov_b32_e32 v81, v205
	v_ashrrev_i32_e32 v77, 31, v76
	v_lshl_add_u64 v[76:77], s[14:15], 0, v[76:77]
	v_mad_u64_u32 v[86:87], s[0:1], v76, s41, v[70:71]
	v_mul_f32_e32 v76, v34, v78
	v_add_u32_e32 v82, s46, v111
	v_mul_f32_e32 v68, v50, v78
	v_mad_i32_i24 v87, v77, s41, v87
	v_lshl_or_b32 v84, v82, 5, v105
	v_ashrrev_i32_e32 v85, 31, v84
	v_lshl_add_u64 v[84:85], v[84:85], 3, s[10:11]
	v_ashrrev_i32_e32 v83, 31, v82
	v_lshl_add_u64 v[82:83], s[14:15], 0, v[82:83]
	v_add_u32_e32 v78, s46, v112
	v_mul_f32_e32 v77, v81, v76
	v_mul_f32_e32 v76, v80, v76
	v_fma_f32 v77, v80, v68, -v77
	v_fmac_f32_e32 v76, v81, v68
	v_cvt_pk_bf16_f32 v68, v77, s0
	v_cvt_pk_bf16_f32 v76, v76, s0
	global_store_short v[86:87], v68, off offset:256
	global_store_short v[86:87], v76, off offset:320
	v_mov_b32_e32 v76, v206
	v_mov_b32_e32 v77, v207
	v_mul_f32_e32 v68, v51, v79
	v_mul_f32_e32 v79, v35, v79
	v_mad_u64_u32 v[84:85], s[0:1], v82, s41, v[70:71]
	v_lshl_or_b32 v80, v78, 5, v105
	v_ashrrev_i32_e32 v81, 31, v80
	v_mad_i32_i24 v85, v83, s41, v85
	v_lshl_add_u64 v[80:81], v[80:81], 3, s[10:11]
	v_mul_f32_e32 v82, v77, v79
	v_mul_f32_e32 v79, v76, v79
	v_fma_f32 v76, v76, v68, -v82
	v_fmac_f32_e32 v79, v77, v68
	v_cvt_pk_bf16_f32 v68, v76, s0
	v_cvt_pk_bf16_f32 v76, v79, s0
	global_store_short v[84:85], v68, off offset:256
	global_store_short v[84:85], v76, off offset:320
	v_mov_b32_e32 v76, v208
	v_mov_b32_e32 v77, v209
	v_ashrrev_i32_e32 v79, 31, v78
	v_lshl_add_u64 v[78:79], s[14:15], 0, v[78:79]
	s_waitcnt lgkmcnt(0)
; DI bf16 f2bf(float a) { return (bf16)(pack2(a, 0.f) & 0xffffu); }
; DI int crow(int i, int g) { return (i & 3) + 8 * (i >> 2) + 4 * g; }
;     ...
;         } else if (d0 == 128) {
;           if (j < 3) {
; #pragma unroll
;             for (int i = 0; i < 16; ++i) {
;               int rl = 32 * w + crow(i, g);
;               int s = (m0 & 2047) + rl;
;               float2 cs = t64[s * 32 + r];
;               float x1 = acc[j][i] * rs[rl], x2 = acc[(j + 1) & 3][i] * rs[rl];
;               bf16* qp = Qb + ((size_t)(bidx * 8 + hh) * 2048 + s) * 192 + 128;
;               qp[r] = f2bf(x1 * cs.x - x2 * cs.y);
;               qp[32 + r] = f2bf(x2 * cs.x + x1 * cs.y);
;             }
;           }
	v_mul_f32_e32 v68, v52, v64
	v_mul_f32_e32 v64, v36, v64
	v_add_u32_e32 v80, s46, v113
	v_mad_u64_u32 v[84:85], s[0:1], v78, s41, v[70:71]
	v_lshl_or_b32 v82, v80, 5, v105
	v_ashrrev_i32_e32 v83, 31, v82
	v_mad_i32_i24 v85, v79, s41, v85
	v_lshl_add_u64 v[82:83], v[82:83], 3, s[10:11]
	v_ashrrev_i32_e32 v81, 31, v80
	v_lshl_add_u64 v[80:81], s[14:15], 0, v[80:81]
	v_mul_f32_e32 v78, v77, v64
	v_mul_f32_e32 v64, v76, v64
	v_fma_f32 v76, v76, v68, -v78
	v_fmac_f32_e32 v64, v77, v68
	v_cvt_pk_bf16_f32 v68, v76, s0
	v_cvt_pk_bf16_f32 v64, v64, s0
	global_store_short v[84:85], v68, off offset:256
	global_store_short v[84:85], v64, off offset:320
	v_mov_b32_e32 v76, v210
	v_mov_b32_e32 v77, v211
	v_mul_f32_e32 v68, v53, v65
	v_mul_f32_e32 v65, v37, v65
	v_add_u32_e32 v64, s46, v114
	v_mad_u64_u32 v[82:83], s[0:1], v80, s41, v[70:71]
	v_lshl_or_b32 v78, v64, 5, v105
	v_ashrrev_i32_e32 v79, 31, v78
	v_mad_i32_i24 v83, v81, s41, v83
	v_lshl_add_u64 v[78:79], v[78:79], 3, s[10:11]
	v_add_u32_e32 v84, s46, v117
	v_lshl_or_b32 v86, v84, 5, v105
	v_ashrrev_i32_e32 v87, 31, v86
	v_lshl_add_u64 v[86:87], v[86:87], 3, s[10:11]
	v_ashrrev_i32_e32 v85, 31, v84
	v_lshl_add_u64 v[84:85], s[14:15], 0, v[84:85]
	v_mul_f32_e32 v80, v77, v65
	v_mul_f32_e32 v65, v76, v65
	v_fma_f32 v76, v76, v68, -v80
	v_fmac_f32_e32 v65, v77, v68
	v_cvt_pk_bf16_f32 v68, v76, s0
	v_cvt_pk_bf16_f32 v65, v65, s0
	global_store_short v[82:83], v68, off offset:256
	global_store_short v[82:83], v65, off offset:320
	v_mov_b32_e32 v76, v212
	v_mov_b32_e32 v77, v213
	v_ashrrev_i32_e32 v65, 31, v64
	v_lshl_add_u64 v[64:65], s[14:15], 0, v[64:65]
	v_mad_u64_u32 v[82:83], s[0:1], v64, s41, v[70:71]
	v_mul_f32_e32 v64, v54, v66
	v_mul_f32_e32 v66, v38, v66
	v_add_u32_e32 v78, s46, v115
	v_mad_i32_i24 v83, v65, s41, v83
	v_lshl_or_b32 v80, v78, 5, v105
	v_ashrrev_i32_e32 v81, 31, v80
	v_lshl_add_u64 v[80:81], v[80:81], 3, s[10:11]
	v_ashrrev_i32_e32 v79, 31, v78
	v_lshl_add_u64 v[78:79], s[14:15], 0, v[78:79]
	v_mul_f32_e32 v65, v77, v66
	v_mul_f32_e32 v66, v76, v66
	v_fma_f32 v65, v76, v64, -v65
	v_fmac_f32_e32 v66, v77, v64
	v_cvt_pk_bf16_f32 v64, v65, s0
	v_cvt_pk_bf16_f32 v65, v66, s0
	global_store_short v[82:83], v64, off offset:256
	global_store_short v[82:83], v65, off offset:320
	v_mov_b32_e32 v64, v214
	v_mov_b32_e32 v65, v215
	v_mul_f32_e32 v66, v55, v67
	v_mul_f32_e32 v67, v39, v67
	v_add_u32_e32 v80, s46, v116
	v_lshl_or_b32 v76, v80, 5, v105
	v_mad_u64_u32 v[82:83], s[0:1], v78, s41, v[70:71]
	v_ashrrev_i32_e32 v77, 31, v76
	v_mad_i32_i24 v83, v79, s41, v83
	v_lshl_add_u64 v[76:77], v[76:77], 3, s[10:11]
	v_ashrrev_i32_e32 v81, 31, v80
	v_lshl_add_u64 v[80:81], s[14:15], 0, v[80:81]
	v_mul_f32_e32 v68, v65, v67
	v_mul_f32_e32 v67, v64, v67
	v_fma_f32 v64, v64, v66, -v68
	v_fmac_f32_e32 v67, v65, v66
	v_cvt_pk_bf16_f32 v64, v64, s0
	v_cvt_pk_bf16_f32 v65, v67, s0
	global_store_short v[82:83], v64, off offset:256
	global_store_short v[82:83], v65, off offset:320
	v_mov_b32_e32 v82, v216
	v_mov_b32_e32 v83, v217
	ds_read_b128 v[64:67], v108 offset:41024
	ds_read_b128 v[76:79], v108 offset:41056
	v_mad_u64_u32 v[88:89], s[0:1], v80, s41, v[70:71]
	v_mad_i32_i24 v89, v81, s41, v89
	s_waitcnt lgkmcnt(1)
; DI bf16 f2bf(float a) { return (bf16)(pack2(a, 0.f) & 0xffffu); }
; DI int crow(int i, int g) { return (i & 3) + 8 * (i >> 2) + 4 * g; }
;     ...
;         } else if (d0 == 128) {
;           if (j < 3) {
; #pragma unroll
;             for (int i = 0; i < 16; ++i) {
;               int rl = 32 * w + crow(i, g);
;               int s = (m0 & 2047) + rl;
;               float2 cs = t64[s * 32 + r];
;               float x1 = acc[j][i] * rs[rl], x2 = acc[(j + 1) & 3][i] * rs[rl];
;               bf16* qp = Qb + ((size_t)(bidx * 8 + hh) * 2048 + s) * 192 + 128;
;               qp[r] = f2bf(x1 * cs.x - x2 * cs.y);
;               qp[32 + r] = f2bf(x2 * cs.x + x1 * cs.y);
;             }
;           }
	v_mul_f32_e32 v68, v56, v64
	v_mul_f32_e32 v64, v40, v64
	v_mul_f32_e32 v80, v83, v64
	v_mul_f32_e32 v64, v82, v64
	v_fma_f32 v80, v82, v68, -v80
	v_fmac_f32_e32 v64, v83, v68
	v_cvt_pk_bf16_f32 v68, v80, s0
	v_cvt_pk_bf16_f32 v64, v64, s0
	global_store_short v[88:89], v68, off offset:256
	global_store_short v[88:89], v64, off offset:320
	v_mov_b32_e32 v80, v218
	v_mov_b32_e32 v81, v219
	v_mul_f32_e32 v68, v57, v65
	v_mul_f32_e32 v65, v41, v65
	v_add_u32_e32 v64, s46, v118
	v_mad_u64_u32 v[86:87], s[0:1], v84, s41, v[70:71]
	v_lshl_or_b32 v82, v64, 5, v105
	v_ashrrev_i32_e32 v83, 31, v82
	v_mad_i32_i24 v87, v85, s41, v87
	v_lshl_add_u64 v[82:83], v[82:83], 3, s[10:11]
	v_mul_f32_e32 v84, v81, v65
	v_mul_f32_e32 v65, v80, v65
	v_fma_f32 v80, v80, v68, -v84
	v_fmac_f32_e32 v65, v81, v68
	v_cvt_pk_bf16_f32 v68, v80, s0
	v_cvt_pk_bf16_f32 v65, v65, s0
	global_store_short v[86:87], v68, off offset:256
	global_store_short v[86:87], v65, off offset:320
	v_mov_b32_e32 v80, v220
	v_mov_b32_e32 v81, v221
	v_ashrrev_i32_e32 v65, 31, v64
	v_lshl_add_u64 v[64:65], s[14:15], 0, v[64:65]
	v_mad_u64_u32 v[86:87], s[0:1], v64, s41, v[70:71]
	v_mul_f32_e32 v64, v58, v66
	v_mul_f32_e32 v66, v42, v66
	v_add_u32_e32 v82, s46, v119
	v_mad_i32_i24 v87, v65, s41, v87
	v_lshl_or_b32 v84, v82, 5, v105
	v_ashrrev_i32_e32 v85, 31, v84
	v_lshl_add_u64 v[84:85], v[84:85], 3, s[10:11]
	v_ashrrev_i32_e32 v83, 31, v82
	v_lshl_add_u64 v[82:83], s[14:15], 0, v[82:83]
	v_mul_f32_e32 v68, v59, v67
	v_mul_f32_e32 v67, v43, v67
	v_mul_f32_e32 v65, v81, v66
	v_mul_f32_e32 v66, v80, v66
	v_fma_f32 v65, v80, v64, -v65
	v_fmac_f32_e32 v66, v81, v64
	v_cvt_pk_bf16_f32 v64, v65, s0
	v_cvt_pk_bf16_f32 v65, v66, s0
	global_store_short v[86:87], v64, off offset:256
	global_store_short v[86:87], v65, off offset:320
	v_mov_b32_e32 v64, v222
	v_mov_b32_e32 v65, v223
	v_add_u32_e32 v66, s46, v120
	v_mad_u64_u32 v[84:85], s[0:1], v82, s41, v[70:71]
	v_lshl_or_b32 v80, v66, 5, v105
	v_ashrrev_i32_e32 v81, 31, v80
	v_mad_i32_i24 v85, v83, s41, v85
	v_lshl_add_u64 v[80:81], v[80:81], 3, s[10:11]
	v_mul_f32_e32 v82, v65, v67
	v_mul_f32_e32 v67, v64, v67
	v_fma_f32 v64, v64, v68, -v82
	v_fmac_f32_e32 v67, v65, v68
	v_cvt_pk_bf16_f32 v64, v64, s0
	v_cvt_pk_bf16_f32 v65, v67, s0
	global_store_short v[84:85], v64, off offset:256
	global_store_short v[84:85], v65, off offset:320
	v_mov_b32_e32 v64, v224
	v_mov_b32_e32 v65, v225
	v_ashrrev_i32_e32 v67, 31, v66
	v_lshl_add_u64 v[66:67], s[14:15], 0, v[66:67]
	v_mad_u64_u32 v[84:85], s[0:1], v66, s41, v[70:71]
	s_waitcnt lgkmcnt(0)
	v_mul_f32_e32 v68, v44, v76
	v_add_u32_e32 v80, s46, v121
	v_mul_f32_e32 v66, v60, v76
	v_mad_i32_i24 v85, v67, s41, v85
	v_lshl_or_b32 v82, v80, 5, v105
	v_ashrrev_i32_e32 v83, 31, v82
	v_lshl_add_u64 v[82:83], v[82:83], 3, s[10:11]
	v_ashrrev_i32_e32 v81, 31, v80
	v_lshl_add_u64 v[80:81], s[14:15], 0, v[80:81]
	v_mul_f32_e32 v67, v65, v68
	v_mul_f32_e32 v68, v64, v68
	v_fma_f32 v64, v64, v66, -v67
	v_fmac_f32_e32 v68, v65, v66
	v_cvt_pk_bf16_f32 v64, v64, s0
	v_cvt_pk_bf16_f32 v65, v68, s0
	global_store_short v[84:85], v64, off offset:256
	global_store_short v[84:85], v65, off offset:320
	v_mov_b32_e32 v64, v226
	v_mov_b32_e32 v65, v227
	v_mul_f32_e32 v68, v45, v77
	v_add_u32_e32 v66, s46, v122
	v_mul_f32_e32 v67, v61, v77
	v_lshl_or_b32 v82, v66, 5, v105
	v_mad_u64_u32 v[84:85], s[0:1], v80, s41, v[70:71]
	v_ashrrev_i32_e32 v83, 31, v82
	v_mad_i32_i24 v85, v81, s41, v85
	v_lshl_add_u64 v[82:83], v[82:83], 3, s[10:11]
	v_mul_f32_e32 v76, v65, v68
	v_mul_f32_e32 v68, v64, v68
	v_fma_f32 v64, v64, v67, -v76
	v_fmac_f32_e32 v68, v65, v67
	v_cvt_pk_bf16_f32 v64, v64, s0
	v_cvt_pk_bf16_f32 v65, v68, s0
	global_store_short v[84:85], v64, off offset:256
	global_store_short v[84:85], v65, off offset:320
	v_mov_b32_e32 v64, v228
	v_mov_b32_e32 v65, v229
	v_ashrrev_i32_e32 v67, 31, v66
	v_lshl_add_u64 v[66:67], s[14:15], 0, v[66:67]
	v_mad_u64_u32 v[82:83], s[0:1], v66, s41, v[70:71]
	v_mul_f32_e32 v68, v46, v78
	v_add_u32_e32 v76, s46, v123
	v_mul_f32_e32 v66, v62, v78
	v_mad_i32_i24 v83, v67, s41, v83
	v_lshl_or_b32 v80, v76, 5, v105
	v_ashrrev_i32_e32 v81, 31, v80
	v_lshl_add_u64 v[80:81], v[80:81], 3, s[10:11]
	v_ashrrev_i32_e32 v77, 31, v76
	v_mul_f32_e32 v67, v65, v68
	v_mul_f32_e32 v68, v64, v68
	v_fma_f32 v64, v64, v66, -v67
	v_fmac_f32_e32 v68, v65, v66
	v_cvt_pk_bf16_f32 v64, v64, s0
	v_cvt_pk_bf16_f32 v65, v68, s0
	global_store_short v[82:83], v64, off offset:256
	global_store_short v[82:83], v65, off offset:320
	v_mov_b32_e32 v64, v230
	v_mov_b32_e32 v65, v231
	v_lshl_add_u64 v[66:67], s[14:15], 0, v[76:77]
	v_mad_u64_u32 v[76:77], s[0:1], v66, s41, v[70:71]
	v_mul_f32_e32 v68, v47, v79
	v_mul_f32_e32 v66, v63, v79
	v_mad_i32_i24 v77, v67, s41, v77
	v_mul_f32_e32 v67, v65, v68
	v_mul_f32_e32 v68, v64, v68
	v_fma_f32 v64, v64, v66, -v67
	v_fmac_f32_e32 v68, v65, v66
	v_cvt_pk_bf16_f32 v64, v64, s0
	v_cvt_pk_bf16_f32 v65, v68, s0
	global_store_short v[76:77], v64, off offset:256
	global_store_short v[76:77], v65, off offset:320

; DI bf16 f2bf(float a) { return (bf16)(pack2(a, 0.f) & 0xffffu); }
; DI int crow(int i, int g) { return (i & 3) + 8 * (i >> 2) + 4 * g; }
;     ...
;         } else if (d0 == 128) {
;           if (j < 3) {
; #pragma unroll
;             for (int i = 0; i < 16; ++i) {
;               int rl = 32 * w + crow(i, g);
;               int s = (m0 & 2047) + rl;
;               float2 cs = t64[s * 32 + r];
;               float x1 = acc[j][i] * rs[rl], x2 = acc[(j + 1) & 3][i] * rs[rl];
;               bf16* qp = Qb + ((size_t)(bidx * 8 + hh) * 2048 + s) * 192 + 128;
;               qp[r] = f2bf(x1 * cs.x - x2 * cs.y);
;               qp[32 + r] = f2bf(x2 * cs.x + x1 * cs.y);
;             }
;           }
.LBB0_333:
	s_sub_i32 s0, s44, 32
	s_mul_hi_i32 s0, s0, 0x2aaaaaab
	s_lshr_b32 s1, s0, 31
	s_ashr_i32 s13, s0, 5
	s_add_i32 s13, s13, s1
	s_mul_i32 s0, s13, 0xffffff40
	s_sub_i32 s0, s0, s43
	s_add_i32 s0, s4, s0
	s_sub_i32 s12, s0, 32
	s_cmpk_lt_i32 s12, 0x80
	s_mov_b64 s[14:15], -1
	s_cbranch_scc1 .LBB0_337
	s_cmpk_lg_i32 s0, 0xa0
	s_cbranch_scc1 .LBB0_336
	v_lshl_or_b32 v32, v102, 5, v105
	v_ashrrev_i32_e32 v33, 31, v32
	v_lshl_add_u64 v[32:33], v[32:33], 3, s[10:11]
	global_load_dwordx2 v[40:41], v[32:33], off
	v_lshl_or_b32 v232, v100, 5, v105
	v_mov_b32_e32 v233, 0
	v_lshl_add_u64 v[232:233], v[232:233], 3, s[10:11]
	global_load_dwordx2 v[202:203], v[232:233], off
	v_lshl_or_b32 v234, v98, 5, v105
	v_mov_b32_e32 v235, 0
	v_lshl_add_u64 v[234:235], v[234:235], 3, s[10:11]
	global_load_dwordx2 v[204:205], v[234:235], off
	v_lshl_or_b32 v232, v96, 5, v105
	v_mov_b32_e32 v233, 0
	v_lshl_add_u64 v[232:233], v[232:233], 3, s[10:11]
	global_load_dwordx2 v[206:207], v[232:233], off
	v_lshl_or_b32 v234, v94, 5, v105
	v_mov_b32_e32 v235, 0
	v_lshl_add_u64 v[234:235], v[234:235], 3, s[10:11]
	global_load_dwordx2 v[208:209], v[234:235], off
	v_lshl_or_b32 v232, v92, 5, v105
	v_mov_b32_e32 v233, 0
	v_lshl_add_u64 v[232:233], v[232:233], 3, s[10:11]
	global_load_dwordx2 v[210:211], v[232:233], off
	v_lshl_or_b32 v234, v90, 5, v105
	v_mov_b32_e32 v235, 0
	v_lshl_add_u64 v[234:235], v[234:235], 3, s[10:11]
	global_load_dwordx2 v[212:213], v[234:235], off
	v_lshl_or_b32 v232, v88, 5, v105
	v_mov_b32_e32 v233, 0
	v_lshl_add_u64 v[232:233], v[232:233], 3, s[10:11]
	global_load_dwordx2 v[214:215], v[232:233], off
	v_lshl_or_b32 v234, v86, 5, v105
	v_mov_b32_e32 v235, 0
	v_lshl_add_u64 v[234:235], v[234:235], 3, s[10:11]
	global_load_dwordx2 v[216:217], v[234:235], off
	v_lshl_or_b32 v232, v84, 5, v105
	v_mov_b32_e32 v233, 0
	v_lshl_add_u64 v[232:233], v[232:233], 3, s[10:11]
	global_load_dwordx2 v[218:219], v[232:233], off
	v_lshl_or_b32 v234, v82, 5, v105
	v_mov_b32_e32 v235, 0
	v_lshl_add_u64 v[234:235], v[234:235], 3, s[10:11]
	global_load_dwordx2 v[220:221], v[234:235], off
	v_lshl_or_b32 v232, v80, 5, v105
	v_mov_b32_e32 v233, 0
	v_lshl_add_u64 v[232:233], v[232:233], 3, s[10:11]
	global_load_dwordx2 v[222:223], v[232:233], off
	v_lshl_or_b32 v234, v78, 5, v105
	v_mov_b32_e32 v235, 0
	v_lshl_add_u64 v[234:235], v[234:235], 3, s[10:11]
	global_load_dwordx2 v[224:225], v[234:235], off
	v_lshl_or_b32 v232, v76, 5, v105
	v_mov_b32_e32 v233, 0
	v_lshl_add_u64 v[232:233], v[232:233], 3, s[10:11]
	global_load_dwordx2 v[226:227], v[232:233], off
	v_lshl_or_b32 v234, v66, 5, v105
	v_mov_b32_e32 v235, 0
	v_lshl_add_u64 v[234:235], v[234:235], 3, s[10:11]
	global_load_dwordx2 v[228:229], v[234:235], off
	v_lshl_or_b32 v232, v64, 5, v105
	v_mov_b32_e32 v233, 0
	v_lshl_add_u64 v[232:233], v[232:233], 3, s[10:11]
	global_load_dwordx2 v[230:231], v[232:233], off
	s_add_i32 s0, s13, s45
	ds_read_b128 v[36:39], v108 offset:40960
	ds_read_b128 v[32:35], v108 offset:40992
	s_ashr_i32 s1, s0, 31
	s_lshl_b64 s[14:15], s[0:1], 11
	v_lshl_add_u64 v[44:45], s[14:15], 0, v[102:103]
	v_mad_u64_u32 v[46:47], s[0:1], v44, s41, v[70:71]
	s_waitcnt lgkmcnt(1)
	v_mul_f32_e32 v44, v16, v36
	v_mul_f32_e32 v36, v0, v36
	v_mad_i32_i24 v47, v45, s41, v47
	v_lshl_or_b32 v42, v100, 5, v105
	v_ashrrev_i32_e32 v43, 31, v42
	v_lshl_add_u64 v[42:43], v[42:43], 3, s[10:11]
	s_waitcnt vmcnt(0)
	v_mul_f32_e32 v45, v41, v36
	v_mul_f32_e32 v36, v40, v36
	v_fma_f32 v40, v40, v44, -v45
	v_fmac_f32_e32 v36, v41, v44
	v_cvt_pk_bf16_f32 v40, v40, s0
	v_cvt_pk_bf16_f32 v36, v36, s0
	global_store_short v[46:47], v40, off offset:256
	global_store_short v[46:47], v36, off offset:320
	v_mov_b32_e32 v40, v202
	v_mov_b32_e32 v41, v203
	v_lshl_add_u64 v[44:45], s[14:15], 0, v[100:101]
	v_mul_f32_e32 v36, v17, v37
	v_mul_f32_e32 v37, v1, v37
	v_mad_u64_u32 v[46:47], s[0:1], v44, s41, v[70:71]
	v_lshl_or_b32 v42, v98, 5, v105
	v_ashrrev_i32_e32 v43, 31, v42
	v_mad_i32_i24 v47, v45, s41, v47
	v_lshl_add_u64 v[42:43], v[42:43], 3, s[10:11]
	v_mul_f32_e32 v44, v41, v37
	v_mul_f32_e32 v37, v40, v37
	v_fma_f32 v40, v40, v36, -v44
	v_fmac_f32_e32 v37, v41, v36
	v_cvt_pk_bf16_f32 v36, v40, s0
	v_cvt_pk_bf16_f32 v37, v37, s0
	global_store_short v[46:47], v36, off offset:256
	global_store_short v[46:47], v37, off offset:320
	v_mov_b32_e32 v36, v204
	v_mov_b32_e32 v37, v205
	v_lshl_add_u64 v[42:43], s[14:15], 0, v[98:99]
	v_mad_u64_u32 v[44:45], s[0:1], v42, s41, v[70:71]
	v_mul_f32_e32 v42, v18, v38
	v_mul_f32_e32 v38, v2, v38
	v_mad_i32_i24 v45, v43, s41, v45
	v_lshl_or_b32 v40, v96, 5, v105
	v_ashrrev_i32_e32 v41, 31, v40
	v_lshl_add_u64 v[40:41], v[40:41], 3, s[10:11]
	v_mul_f32_e32 v43, v37, v38
	v_mul_f32_e32 v38, v36, v38
	v_fma_f32 v36, v36, v42, -v43
	v_fmac_f32_e32 v38, v37, v42
	v_cvt_pk_bf16_f32 v36, v36, s0
	v_cvt_pk_bf16_f32 v37, v38, s0
	global_store_short v[44:45], v36, off offset:256
	global_store_short v[44:45], v37, off offset:320
	v_mov_b32_e32 v36, v206
	v_mov_b32_e32 v37, v207
	v_lshl_add_u64 v[42:43], s[14:15], 0, v[96:97]
	v_mul_f32_e32 v38, v19, v39
	v_mul_f32_e32 v39, v3, v39
	v_mad_u64_u32 v[44:45], s[0:1], v42, s41, v[70:71]
	v_lshl_or_b32 v40, v94, 5, v105
	v_ashrrev_i32_e32 v41, 31, v40
	v_mad_i32_i24 v45, v43, s41, v45
	v_lshl_add_u64 v[40:41], v[40:41], 3, s[10:11]
	v_mul_f32_e32 v42, v37, v39
	v_mul_f32_e32 v39, v36, v39
	v_fma_f32 v36, v36, v38, -v42
	v_fmac_f32_e32 v39, v37, v38
	v_cvt_pk_bf16_f32 v36, v36, s0
	v_cvt_pk_bf16_f32 v37, v39, s0
	global_store_short v[44:45], v36, off offset:256
	global_store_short v[44:45], v37, off offset:320
	v_mov_b32_e32 v36, v208
	v_mov_b32_e32 v37, v209
	v_lshl_add_u64 v[40:41], s[14:15], 0, v[94:95]
	v_mad_u64_u32 v[42:43], s[0:1], v40, s41, v[70:71]
	s_waitcnt lgkmcnt(0)
; DI bf16 f2bf(float a) { return (bf16)(pack2(a, 0.f) & 0xffffu); }
; DI int crow(int i, int g) { return (i & 3) + 8 * (i >> 2) + 4 * g; }
;     ...
;         } else if (d0 == 128) {
;           if (j < 3) {
; #pragma unroll
;             for (int i = 0; i < 16; ++i) {
;               int rl = 32 * w + crow(i, g);
;               int s = (m0 & 2047) + rl;
;               float2 cs = t64[s * 32 + r];
;               float x1 = acc[j][i] * rs[rl], x2 = acc[(j + 1) & 3][i] * rs[rl];
;               bf16* qp = Qb + ((size_t)(bidx * 8 + hh) * 2048 + s) * 192 + 128;
;               qp[r] = f2bf(x1 * cs.x - x2 * cs.y);
;               qp[32 + r] = f2bf(x2 * cs.x + x1 * cs.y);
;             }
;           }
	v_mul_f32_e32 v40, v20, v32
	v_mul_f32_e32 v32, v4, v32
	v_mad_i32_i24 v43, v41, s41, v43
	v_lshl_or_b32 v38, v92, 5, v105
	v_ashrrev_i32_e32 v39, 31, v38
	v_lshl_add_u64 v[38:39], v[38:39], 3, s[10:11]
	v_lshl_add_u64 v[44:45], s[14:15], 0, v[86:87]
	v_mul_f32_e32 v41, v37, v32
	v_mul_f32_e32 v32, v36, v32
	v_fma_f32 v36, v36, v40, -v41
	v_fmac_f32_e32 v32, v37, v40
	v_cvt_pk_bf16_f32 v36, v36, s0
	v_cvt_pk_bf16_f32 v32, v32, s0
	global_store_short v[42:43], v36, off offset:256
	global_store_short v[42:43], v32, off offset:320
	v_mov_b32_e32 v36, v210
	v_mov_b32_e32 v37, v211
	v_lshl_add_u64 v[40:41], s[14:15], 0, v[92:93]
	v_mul_f32_e32 v32, v21, v33
	v_mul_f32_e32 v33, v5, v33
	v_mad_u64_u32 v[42:43], s[0:1], v40, s41, v[70:71]
	v_lshl_or_b32 v38, v90, 5, v105
	v_ashrrev_i32_e32 v39, 31, v38
	v_mad_i32_i24 v43, v41, s41, v43
	v_lshl_add_u64 v[38:39], v[38:39], 3, s[10:11]
	v_mul_f32_e32 v40, v37, v33
	v_mul_f32_e32 v33, v36, v33
	v_fma_f32 v36, v36, v32, -v40
	v_fmac_f32_e32 v33, v37, v32
	v_cvt_pk_bf16_f32 v32, v36, s0
	v_cvt_pk_bf16_f32 v33, v33, s0
	global_store_short v[42:43], v32, off offset:256
	global_store_short v[42:43], v33, off offset:320
	v_mov_b32_e32 v32, v212
	v_mov_b32_e32 v33, v213
	v_lshl_add_u64 v[38:39], s[14:15], 0, v[90:91]
	v_mad_u64_u32 v[40:41], s[0:1], v38, s41, v[70:71]
	v_mul_f32_e32 v38, v22, v34
	v_mul_f32_e32 v34, v6, v34
	v_mad_i32_i24 v41, v39, s41, v41
	v_lshl_or_b32 v36, v88, 5, v105
	v_ashrrev_i32_e32 v37, 31, v36
	v_lshl_add_u64 v[36:37], v[36:37], 3, s[10:11]
	v_lshl_or_b32 v42, v84, 5, v105
	v_ashrrev_i32_e32 v43, 31, v42
	v_lshl_add_u64 v[42:43], v[42:43], 3, s[10:11]
	v_mul_f32_e32 v39, v33, v34
	v_mul_f32_e32 v34, v32, v34
	v_fma_f32 v32, v32, v38, -v39
	v_fmac_f32_e32 v34, v33, v38
	v_cvt_pk_bf16_f32 v32, v32, s0
	v_cvt_pk_bf16_f32 v33, v34, s0
	global_store_short v[40:41], v32, off offset:256
	global_store_short v[40:41], v33, off offset:320
	v_mov_b32_e32 v32, v214
	v_mov_b32_e32 v33, v215
	v_lshl_add_u64 v[38:39], s[14:15], 0, v[88:89]
	v_mul_f32_e32 v34, v23, v35
	v_mul_f32_e32 v35, v7, v35
	v_mad_u64_u32 v[40:41], s[0:1], v38, s41, v[70:71]
	v_lshl_or_b32 v36, v86, 5, v105
	v_ashrrev_i32_e32 v37, 31, v36
	v_mad_i32_i24 v41, v39, s41, v41
	v_lshl_add_u64 v[36:37], v[36:37], 3, s[10:11]
	v_mul_f32_e32 v38, v33, v35
	v_mul_f32_e32 v35, v32, v35
	v_fma_f32 v32, v32, v34, -v38
	v_fmac_f32_e32 v35, v33, v34
	v_cvt_pk_bf16_f32 v32, v32, s0
	v_cvt_pk_bf16_f32 v33, v35, s0
	global_store_short v[40:41], v32, off offset:256
	global_store_short v[40:41], v33, off offset:320
	v_mov_b32_e32 v40, v216
	v_mov_b32_e32 v41, v217
	ds_read_b128 v[32:35], v108 offset:41024
	ds_read_b128 v[36:39], v108 offset:41056
	v_mad_u64_u32 v[46:47], s[0:1], v44, s41, v[70:71]
	v_mad_i32_i24 v47, v45, s41, v47
	s_waitcnt lgkmcnt(1)
; DI bf16 f2bf(float a) { return (bf16)(pack2(a, 0.f) & 0xffffu); }
; DI int crow(int i, int g) { return (i & 3) + 8 * (i >> 2) + 4 * g; }
;     ...
;         } else if (d0 == 128) {
;           if (j < 3) {
; #pragma unroll
;             for (int i = 0; i < 16; ++i) {
;               int rl = 32 * w + crow(i, g);
;               int s = (m0 & 2047) + rl;
;               float2 cs = t64[s * 32 + r];
;               float x1 = acc[j][i] * rs[rl], x2 = acc[(j + 1) & 3][i] * rs[rl];
;               bf16* qp = Qb + ((size_t)(bidx * 8 + hh) * 2048 + s) * 192 + 128;
;               qp[r] = f2bf(x1 * cs.x - x2 * cs.y);
;               qp[32 + r] = f2bf(x2 * cs.x + x1 * cs.y);
;             }
;           }
	v_mul_f32_e32 v44, v24, v32
	v_mul_f32_e32 v32, v8, v32
	v_mul_f32_e32 v45, v41, v32
	v_mul_f32_e32 v32, v40, v32
	v_fma_f32 v40, v40, v44, -v45
	v_fmac_f32_e32 v32, v41, v44
	v_cvt_pk_bf16_f32 v40, v40, s0
	v_cvt_pk_bf16_f32 v32, v32, s0
	global_store_short v[46:47], v40, off offset:256
	global_store_short v[46:47], v32, off offset:320
	v_mov_b32_e32 v40, v218
	v_mov_b32_e32 v41, v219
	v_lshl_add_u64 v[44:45], s[14:15], 0, v[84:85]
	v_mul_f32_e32 v32, v25, v33
	v_mul_f32_e32 v33, v9, v33
	v_mad_u64_u32 v[46:47], s[0:1], v44, s41, v[70:71]
	v_lshl_or_b32 v42, v82, 5, v105
	v_ashrrev_i32_e32 v43, 31, v42
	v_mad_i32_i24 v47, v45, s41, v47
	v_lshl_add_u64 v[42:43], v[42:43], 3, s[10:11]
	v_mul_f32_e32 v44, v41, v33
	v_mul_f32_e32 v33, v40, v33
	v_fma_f32 v40, v40, v32, -v44
	v_fmac_f32_e32 v33, v41, v32
	v_cvt_pk_bf16_f32 v32, v40, s0
	v_cvt_pk_bf16_f32 v33, v33, s0
	global_store_short v[46:47], v32, off offset:256
	global_store_short v[46:47], v33, off offset:320
	v_mov_b32_e32 v32, v220
	v_mov_b32_e32 v33, v221
	v_lshl_add_u64 v[42:43], s[14:15], 0, v[82:83]
	v_mad_u64_u32 v[44:45], s[0:1], v42, s41, v[70:71]
	v_mul_f32_e32 v42, v26, v34
	v_mul_f32_e32 v34, v10, v34
	v_mad_i32_i24 v45, v43, s41, v45
	v_lshl_or_b32 v40, v80, 5, v105
	v_ashrrev_i32_e32 v41, 31, v40
	v_lshl_add_u64 v[40:41], v[40:41], 3, s[10:11]
	v_mul_f32_e32 v43, v33, v34
	v_mul_f32_e32 v34, v32, v34
	v_fma_f32 v32, v32, v42, -v43
	v_fmac_f32_e32 v34, v33, v42
	v_cvt_pk_bf16_f32 v32, v32, s0
	v_cvt_pk_bf16_f32 v33, v34, s0
	global_store_short v[44:45], v32, off offset:256
	global_store_short v[44:45], v33, off offset:320
	v_mov_b32_e32 v32, v222
	v_mov_b32_e32 v33, v223
	v_lshl_add_u64 v[42:43], s[14:15], 0, v[80:81]
	v_mul_f32_e32 v34, v27, v35
	v_mul_f32_e32 v35, v11, v35
	v_mad_u64_u32 v[44:45], s[0:1], v42, s41, v[70:71]
	v_lshl_or_b32 v40, v78, 5, v105
	v_ashrrev_i32_e32 v41, 31, v40
	v_mad_i32_i24 v45, v43, s41, v45
	v_lshl_add_u64 v[40:41], v[40:41], 3, s[10:11]
	v_mul_f32_e32 v42, v33, v35
	v_mul_f32_e32 v35, v32, v35
	v_fma_f32 v32, v32, v34, -v42
	v_fmac_f32_e32 v35, v33, v34
	v_cvt_pk_bf16_f32 v32, v32, s0
	v_cvt_pk_bf16_f32 v33, v35, s0
	global_store_short v[44:45], v32, off offset:256
	global_store_short v[44:45], v33, off offset:320
	v_mov_b32_e32 v32, v224
	v_mov_b32_e32 v33, v225
	v_lshl_add_u64 v[40:41], s[14:15], 0, v[78:79]
	v_mad_u64_u32 v[42:43], s[0:1], v40, s41, v[70:71]
	s_waitcnt lgkmcnt(0)
	v_mul_f32_e32 v40, v28, v36
	v_mul_f32_e32 v36, v12, v36
	v_mad_i32_i24 v43, v41, s41, v43
	v_lshl_or_b32 v34, v76, 5, v105
	v_ashrrev_i32_e32 v35, 31, v34
	v_lshl_add_u64 v[34:35], v[34:35], 3, s[10:11]
	v_mul_f32_e32 v41, v33, v36
	v_mul_f32_e32 v36, v32, v36
	v_fma_f32 v32, v32, v40, -v41
	v_fmac_f32_e32 v36, v33, v40
	v_cvt_pk_bf16_f32 v32, v32, s0
	v_cvt_pk_bf16_f32 v33, v36, s0
	global_store_short v[42:43], v32, off offset:256
	global_store_short v[42:43], v33, off offset:320
	v_mov_b32_e32 v32, v226
	v_mov_b32_e32 v33, v227
	v_lshl_add_u64 v[40:41], s[14:15], 0, v[76:77]
	v_mul_f32_e32 v36, v29, v37
	v_mul_f32_e32 v37, v13, v37
	v_mad_u64_u32 v[42:43], s[0:1], v40, s41, v[70:71]
	v_lshl_or_b32 v34, v66, 5, v105
	v_ashrrev_i32_e32 v35, 31, v34
	v_mad_i32_i24 v43, v41, s41, v43
	v_lshl_add_u64 v[34:35], v[34:35], 3, s[10:11]
	v_mul_f32_e32 v40, v33, v37
	v_mul_f32_e32 v37, v32, v37
	v_fma_f32 v32, v32, v36, -v40
	v_fmac_f32_e32 v37, v33, v36
	v_cvt_pk_bf16_f32 v32, v32, s0
	v_cvt_pk_bf16_f32 v33, v37, s0
	global_store_short v[42:43], v32, off offset:256
	global_store_short v[42:43], v33, off offset:320
	v_mov_b32_e32 v32, v228
	v_mov_b32_e32 v33, v229
	v_lshl_add_u64 v[36:37], s[14:15], 0, v[66:67]
	v_mad_u64_u32 v[40:41], s[0:1], v36, s41, v[70:71]
	v_mul_f32_e32 v36, v30, v38
	v_mul_f32_e32 v38, v14, v38
	v_mad_i32_i24 v41, v37, s41, v41
	v_lshl_or_b32 v34, v64, 5, v105
	v_ashrrev_i32_e32 v35, 31, v34
	v_lshl_add_u64 v[34:35], v[34:35], 3, s[10:11]
	v_mul_f32_e32 v37, v33, v38
	v_mul_f32_e32 v38, v32, v38
	v_fma_f32 v32, v32, v36, -v37
	v_fmac_f32_e32 v38, v33, v36
	v_cvt_pk_bf16_f32 v32, v32, s0
	v_cvt_pk_bf16_f32 v33, v38, s0
	global_store_short v[40:41], v32, off offset:256
	global_store_short v[40:41], v33, off offset:320
	v_mov_b32_e32 v32, v230
	v_mov_b32_e32 v33, v231
	v_lshl_add_u64 v[34:35], s[14:15], 0, v[64:65]
	v_mad_u64_u32 v[36:37], s[0:1], v34, s41, v[70:71]
	v_mul_f32_e32 v38, v15, v39
	v_mul_f32_e32 v34, v31, v39
	v_mad_i32_i24 v37, v35, s41, v37
	v_mul_f32_e32 v35, v33, v38
	v_mul_f32_e32 v38, v32, v38
	v_fma_f32 v32, v32, v34, -v35
	v_fmac_f32_e32 v38, v33, v34
	v_cvt_pk_bf16_f32 v32, v32, s0
	v_cvt_pk_bf16_f32 v33, v38, s0
	global_store_short v[36:37], v32, off offset:256
	global_store_short v[36:37], v33, off offset:320
